# grid barrier: non-leader workgroups poll the global generation word directly (one release hop less); first-barrier census loads issued together
# speedup vs baseline: 1.0253x; 1.0090x over previous
; __device__ __forceinline__ unsigned xb_ld(unsigned* p)              { return __hip_atomic_load(p, __ATOMIC_RELAXED, __HIP_MEMORY_SCOPE_AGENT); }
; __device__ __forceinline__ void xcd_barrier_complete(unsigned* bar, unsigned x, unsigned& nloc, unsigned& nx) {
;     const unsigned G = gridDim.x * gridDim.y * gridDim.z;
;     unsigned sum, cnt, mine, sp = 0u;
;     for (;;) {
;         sum = 0u; cnt = 0u; mine = 0u;
; #pragma unroll
;         for (unsigned j = 0; j < 16; ++j) { const unsigned c = xb_ld(&bar[XB_XCNT(j)]); sum += c; cnt += (c > 0u) ? 1u : 0u; mine = (j == x) ? c : mine; }
;         if (sum == G) break;
;         __builtin_amdgcn_s_sleep(1);
;         if ((++sp & 255u) == 0u) { if (xb_ld(&bar[XB_TMO])) break; if (sp > XB_SPIN_CAP) { atomicAdd(&bar[XB_TMO], 1u); break; } }
;     }
.LBB0_37:
	v_readlane_b32 s14, v249, 5
	v_readlane_b32 s15, v249, 6
	s_mov_b64 s[18:19], -1
	s_mov_b64 s[20:21], -1
	s_waitcnt lgkmcnt(0)
	s_nop 1
	global_load_dword v0, v16, s[14:15] sc1
	global_load_dword v1, v16, s[14:15] offset:256 sc1
	global_load_dword v2, v16, s[14:15] offset:512 sc1
	global_load_dword v3, v16, s[14:15] offset:768 sc1
	global_load_dword v4, v16, s[14:15] offset:1024 sc1
	global_load_dword v5, v16, s[14:15] offset:1280 sc1
	global_load_dword v6, v16, s[14:15] offset:1536 sc1
	global_load_dword v7, v16, s[14:15] offset:1792 sc1
	global_load_dword v8, v16, s[14:15] offset:2048 sc1
	global_load_dword v9, v16, s[14:15] offset:2304 sc1
	global_load_dword v10, v16, s[14:15] offset:2560 sc1
	global_load_dword v11, v16, s[14:15] offset:2816 sc1
	global_load_dword v12, v16, s[14:15] offset:3072 sc1
	global_load_dword v13, v16, s[14:15] offset:3328 sc1
	global_load_dword v14, v16, s[14:15] offset:3584 sc1
	global_load_dword v15, v16, s[14:15] offset:3840 sc1
	s_waitcnt vmcnt(0)
	v_add_u32_e32 v17, v1, v0
	v_add_u32_e32 v17, v17, v2
	v_add_u32_e32 v17, v17, v3
	v_add_u32_e32 v17, v17, v4
	v_add_u32_e32 v17, v17, v5
	v_add_u32_e32 v17, v17, v6
	v_add_u32_e32 v17, v17, v7
	v_add_u32_e32 v17, v17, v8
	v_add_u32_e32 v17, v17, v9
	v_add_u32_e32 v17, v17, v10
	v_add_u32_e32 v17, v17, v11
	v_add_u32_e32 v17, v17, v12
	v_add_u32_e32 v17, v17, v13
	v_add_u32_e32 v17, v17, v14
	v_add_u32_e32 v17, v17, v15
	v_cmp_eq_u32_e32 vcc, s30, v17
	s_cbranch_vccnz .LBB0_36
	s_and_b32 s5, s3, 0xff
	s_cmp_eq_u32 s5, 0
	s_mov_b64 s[22:23], -1
	s_sleep 1
	s_cbranch_scc1 .LBB0_41
	s_and_b64 vcc, exec, s[22:23]
	s_cbranch_vccz .LBB0_36

; __device__ __forceinline__ unsigned xb_ld(unsigned* p)              { return __hip_atomic_load(p, __ATOMIC_RELAXED, __HIP_MEMORY_SCOPE_AGENT); }
; __device__ __forceinline__ unsigned xb_add(unsigned* p, unsigned v) { return __hip_atomic_fetch_add(p, v, __ATOMIC_RELAXED, __HIP_MEMORY_SCOPE_AGENT); }
; #define XB_SPIN(cond, bar) do { unsigned _sp = 0; while (cond) { __builtin_amdgcn_s_sleep(1); \
;     if ((++_sp & 255u) == 0u) { if (xb_ld(&(bar)[XB_TMO])) break; if (_sp > XB_SPIN_CAP) { atomicAdd(&(bar)[XB_TMO], 1u); break; } } } } while (0)
; __device__ __forceinline__ void xcd_barrier(const XcdBarrier& b) {
;     ...
;         const unsigned old = xb_add(&bar[XB_XSUB(b.x)], 1u);
;         const unsigned gen = old / nloc;
;         if (old + 1u == (gen + 1u) * nloc) {
;             __builtin_amdgcn_fence(__ATOMIC_RELEASE, "agent");
;             asm volatile("s_waitcnt vmcnt(0)" ::: "memory");
;             const unsigned og = xb_add(&bar[XB_TOP], 1u);
;             const unsigned tg = og / nx;
;             if (og + 1u == (tg + 1u) * nx) xb_add(&bar[XB_TOPGEN], 1u);
;             else XB_SPIN(xb_ld(&bar[XB_TOPGEN]) == tg, bar);
;             __builtin_amdgcn_fence(__ATOMIC_ACQUIRE, "agent");
;             xb_add(&bar[XB_XGEN(b.x)], 1u);
;             asm volatile("s_waitcnt vmcnt(0)" ::: "memory");
;         } else {
;             XB_SPIN(xb_ld(&bar[XB_XGEN(b.x)]) == gen, bar);
.LBB0_51:
	s_or_b64 exec, exec, s[18:19]
	v_cvt_f32_u32_e32 v4, v2
	s_waitcnt vmcnt(0)
	v_readfirstlane_b32 s3, v3
	v_sub_u32_e32 v3, 0, v2
	v_rcp_iflag_f32_e32 v4, v4
	v_add_u32_e32 v5, s3, v1
	v_mul_f32_e32 v4, 0x4f7ffffe, v4
	v_cvt_u32_f32_e32 v4, v4
	v_mul_lo_u32 v1, v3, v4
	v_mul_hi_u32 v1, v4, v1
	v_add_u32_e32 v1, v4, v1
	v_mul_hi_u32 v1, v5, v1
	v_mul_lo_u32 v3, v1, v2
	v_sub_u32_e32 v3, v5, v3
	v_add_u32_e32 v4, 1, v1
	v_sub_u32_e32 v6, v3, v2
	v_cmp_ge_u32_e32 vcc, v3, v2
	s_nop 1
	v_cndmask_b32_e32 v1, v1, v4, vcc
	v_cndmask_b32_e32 v3, v3, v6, vcc
	v_add_u32_e32 v4, 1, v1
	v_cmp_ge_u32_e32 vcc, v3, v2
	v_add_u32_e32 v3, 1, v5
	s_nop 0
	v_cndmask_b32_e32 v1, v1, v4, vcc
	v_mul_lo_u32 v4, v2, v1
	v_add_u32_e32 v2, v4, v2
	v_cmp_ne_u32_e32 vcc, v3, v2
	s_and_saveexec_b64 s[16:17], vcc
	s_xor_b64 s[18:19], exec, s[16:17]
	s_cbranch_execz .LBB0_65
	s_waitcnt lgkmcnt(0)
	v_mov_b32_e32 v0, 0
	global_load_dword v2, v0, s[26:27] sc1
	s_waitcnt vmcnt(0)
	v_cmp_eq_u32_e32 vcc, v2, v1
	s_and_saveexec_b64 s[20:21], vcc
	s_cbranch_execz .LBB0_64
	s_mov_b32 s3, 1
	s_mov_b64 s[22:23], 0
	s_branch .LBB0_55

.LBB0_57:
	global_load_dword v2, v0, s[26:27] sc1
	s_add_i32 s3, s3, 1
	s_mov_b64 s[40:41], -1
	s_waitcnt vmcnt(0)
	v_cmp_ne_u32_e32 vcc, v2, v1
	s_orn2_b64 s[38:39], vcc, exec
	s_branch .LBB0_54

; __device__ __forceinline__ unsigned xb_ld(unsigned* p)              { return __hip_atomic_load(p, __ATOMIC_RELAXED, __HIP_MEMORY_SCOPE_AGENT); }
; __device__ __forceinline__ unsigned xb_add(unsigned* p, unsigned v) { return __hip_atomic_fetch_add(p, v, __ATOMIC_RELAXED, __HIP_MEMORY_SCOPE_AGENT); }
; #define XB_SPIN(cond, bar) do { unsigned _sp = 0; while (cond) { __builtin_amdgcn_s_sleep(1); \
;     if ((++_sp & 255u) == 0u) { if (xb_ld(&(bar)[XB_TMO])) break; if (_sp > XB_SPIN_CAP) { atomicAdd(&(bar)[XB_TMO], 1u); break; } } } } while (0)
; __device__ __forceinline__ void xcd_barrier(const XcdBarrier& b) {
;     ...
;         const unsigned old = xb_add(&bar[XB_XSUB(b.x)], 1u);
;         const unsigned gen = old / nloc;
;         if (old + 1u == (gen + 1u) * nloc) {
;             __builtin_amdgcn_fence(__ATOMIC_RELEASE, "agent");
;             asm volatile("s_waitcnt vmcnt(0)" ::: "memory");
;             const unsigned og = xb_add(&bar[XB_TOP], 1u);
;             const unsigned tg = og / nx;
;             if (og + 1u == (tg + 1u) * nx) xb_add(&bar[XB_TOPGEN], 1u);
;             else XB_SPIN(xb_ld(&bar[XB_TOPGEN]) == tg, bar);
;             __builtin_amdgcn_fence(__ATOMIC_ACQUIRE, "agent");
;             xb_add(&bar[XB_XGEN(b.x)], 1u);
;             asm volatile("s_waitcnt vmcnt(0)" ::: "memory");
;         } else {
;             XB_SPIN(xb_ld(&bar[XB_XGEN(b.x)]) == gen, bar);
.LBB0_182:
	s_or_b64 exec, exec, s[18:19]
	v_cvt_f32_u32_e32 v4, v2
	s_waitcnt vmcnt(0)
	v_readfirstlane_b32 s5, v3
	v_sub_u32_e32 v3, 0, v2
	v_rcp_iflag_f32_e32 v4, v4
	v_add_u32_e32 v5, s5, v1
	v_mul_f32_e32 v4, 0x4f7ffffe, v4
	v_cvt_u32_f32_e32 v4, v4
	v_mul_lo_u32 v1, v3, v4
	v_mul_hi_u32 v1, v4, v1
	v_add_u32_e32 v1, v4, v1
	v_mul_hi_u32 v1, v5, v1
	v_mul_lo_u32 v3, v1, v2
	v_sub_u32_e32 v3, v5, v3
	v_add_u32_e32 v4, 1, v1
	v_cmp_ge_u32_e32 vcc, v3, v2
	s_nop 1
	v_cndmask_b32_e32 v1, v1, v4, vcc
	v_sub_u32_e32 v4, v3, v2
	v_cndmask_b32_e32 v3, v3, v4, vcc
	v_add_u32_e32 v4, 1, v1
	v_cmp_ge_u32_e32 vcc, v3, v2
	v_add_u32_e32 v3, 1, v5
	s_nop 0
	v_cndmask_b32_e32 v1, v1, v4, vcc
	v_mul_lo_u32 v4, v2, v1
	v_add_u32_e32 v2, v4, v2
	v_cmp_ne_u32_e32 vcc, v3, v2
	s_and_saveexec_b64 s[14:15], vcc
	s_xor_b64 s[18:19], exec, s[14:15]
	s_cbranch_execz .LBB0_196
	s_waitcnt lgkmcnt(0)
	v_mov_b32_e32 v0, 0
	global_load_dword v2, v0, s[26:27] sc1
	s_waitcnt vmcnt(0)
	v_cmp_eq_u32_e32 vcc, v2, v1
	s_and_saveexec_b64 s[22:23], vcc
	s_cbranch_execz .LBB0_195
	s_mov_b32 s5, 1
	s_mov_b64 s[36:37], 0
	s_branch .LBB0_186

.LBB0_188:
	global_load_dword v2, v0, s[26:27] sc1
	s_add_i32 s5, s5, 1
	s_mov_b64 s[42:43], -1
	s_waitcnt vmcnt(0)
	v_cmp_ne_u32_e32 vcc, v2, v1
	s_orn2_b64 s[40:41], vcc, exec
	s_branch .LBB0_185

; __device__ __forceinline__ unsigned xb_ld(unsigned* p)              { return __hip_atomic_load(p, __ATOMIC_RELAXED, __HIP_MEMORY_SCOPE_AGENT); }
; __device__ __forceinline__ unsigned xb_add(unsigned* p, unsigned v) { return __hip_atomic_fetch_add(p, v, __ATOMIC_RELAXED, __HIP_MEMORY_SCOPE_AGENT); }
; #define XB_SPIN(cond, bar) do { unsigned _sp = 0; while (cond) { __builtin_amdgcn_s_sleep(1); \
;     if ((++_sp & 255u) == 0u) { if (xb_ld(&(bar)[XB_TMO])) break; if (_sp > XB_SPIN_CAP) { atomicAdd(&(bar)[XB_TMO], 1u); break; } } } } while (0)
; __device__ __forceinline__ void xcd_barrier(const XcdBarrier& b) {
;     ...
;         const unsigned old = xb_add(&bar[XB_XSUB(b.x)], 1u);
;         const unsigned gen = old / nloc;
;         if (old + 1u == (gen + 1u) * nloc) {
;             __builtin_amdgcn_fence(__ATOMIC_RELEASE, "agent");
;             asm volatile("s_waitcnt vmcnt(0)" ::: "memory");
;             const unsigned og = xb_add(&bar[XB_TOP], 1u);
;             const unsigned tg = og / nx;
;             if (og + 1u == (tg + 1u) * nx) xb_add(&bar[XB_TOPGEN], 1u);
;             else XB_SPIN(xb_ld(&bar[XB_TOPGEN]) == tg, bar);
;             __builtin_amdgcn_fence(__ATOMIC_ACQUIRE, "agent");
;             xb_add(&bar[XB_XGEN(b.x)], 1u);
;             asm volatile("s_waitcnt vmcnt(0)" ::: "memory");
;         } else {
;             XB_SPIN(xb_ld(&bar[XB_XGEN(b.x)]) == gen, bar);
.LBB0_364:
	s_or_b64 exec, exec, s[18:19]
	v_cvt_f32_u32_e32 v4, v2
	s_waitcnt vmcnt(0)
	v_readfirstlane_b32 s5, v3
	v_sub_u32_e32 v3, 0, v2
	v_rcp_iflag_f32_e32 v4, v4
	v_add_u32_e32 v5, s5, v1
	v_mul_f32_e32 v4, 0x4f7ffffe, v4
	v_cvt_u32_f32_e32 v4, v4
	v_mul_lo_u32 v1, v3, v4
	v_mul_hi_u32 v1, v4, v1
	v_add_u32_e32 v1, v4, v1
	v_mul_hi_u32 v1, v5, v1
	v_mul_lo_u32 v3, v1, v2
	v_sub_u32_e32 v3, v5, v3
	v_add_u32_e32 v4, 1, v1
	v_cmp_ge_u32_e32 vcc, v3, v2
	s_nop 1
	v_cndmask_b32_e32 v1, v1, v4, vcc
	v_sub_u32_e32 v4, v3, v2
	v_cndmask_b32_e32 v3, v3, v4, vcc
	v_add_u32_e32 v4, 1, v1
	v_cmp_ge_u32_e32 vcc, v3, v2
	v_add_u32_e32 v3, 1, v5
	s_nop 0
	v_cndmask_b32_e32 v1, v1, v4, vcc
	v_mul_lo_u32 v4, v2, v1
	v_add_u32_e32 v2, v4, v2
	v_cmp_ne_u32_e32 vcc, v3, v2
	s_and_saveexec_b64 s[14:15], vcc
	s_xor_b64 s[18:19], exec, s[14:15]
	s_cbranch_execz .LBB0_378
	s_waitcnt lgkmcnt(0)
	v_mov_b32_e32 v0, 0
	global_load_dword v2, v0, s[26:27] sc1
	s_waitcnt vmcnt(0)
	v_cmp_eq_u32_e32 vcc, v2, v1
	s_and_saveexec_b64 s[36:37], vcc
	s_cbranch_execz .LBB0_377
	s_mov_b32 s5, 1
	s_mov_b64 s[38:39], 0
	s_branch .LBB0_368

.LBB0_370:
	global_load_dword v2, v0, s[26:27] sc1
	s_add_i32 s5, s5, 1
	s_mov_b64 s[44:45], -1
	s_waitcnt vmcnt(0)
	v_cmp_ne_u32_e32 vcc, v2, v1
	s_orn2_b64 s[42:43], vcc, exec
	s_branch .LBB0_367

; __device__ __forceinline__ unsigned xb_ld(unsigned* p)              { return __hip_atomic_load(p, __ATOMIC_RELAXED, __HIP_MEMORY_SCOPE_AGENT); }
; __device__ __forceinline__ unsigned xb_add(unsigned* p, unsigned v) { return __hip_atomic_fetch_add(p, v, __ATOMIC_RELAXED, __HIP_MEMORY_SCOPE_AGENT); }
; #define XB_SPIN(cond, bar) do { unsigned _sp = 0; while (cond) { __builtin_amdgcn_s_sleep(1); \
;     if ((++_sp & 255u) == 0u) { if (xb_ld(&(bar)[XB_TMO])) break; if (_sp > XB_SPIN_CAP) { atomicAdd(&(bar)[XB_TMO], 1u); break; } } } } while (0)
; __device__ __forceinline__ void xcd_barrier(const XcdBarrier& b) {
;     ...
;         const unsigned old = xb_add(&bar[XB_XSUB(b.x)], 1u);
;         const unsigned gen = old / nloc;
;         if (old + 1u == (gen + 1u) * nloc) {
;             __builtin_amdgcn_fence(__ATOMIC_RELEASE, "agent");
;             asm volatile("s_waitcnt vmcnt(0)" ::: "memory");
;             const unsigned og = xb_add(&bar[XB_TOP], 1u);
;             const unsigned tg = og / nx;
;             if (og + 1u == (tg + 1u) * nx) xb_add(&bar[XB_TOPGEN], 1u);
;             else XB_SPIN(xb_ld(&bar[XB_TOPGEN]) == tg, bar);
;             __builtin_amdgcn_fence(__ATOMIC_ACQUIRE, "agent");
;             xb_add(&bar[XB_XGEN(b.x)], 1u);
;             asm volatile("s_waitcnt vmcnt(0)" ::: "memory");
;         } else {
;             XB_SPIN(xb_ld(&bar[XB_XGEN(b.x)]) == gen, bar);
.LBB0_493:
	s_or_b64 exec, exec, s[18:19]
	v_cvt_f32_u32_e32 v4, v2
	s_waitcnt vmcnt(0)
	v_readfirstlane_b32 s5, v3
	v_sub_u32_e32 v3, 0, v2
	v_rcp_iflag_f32_e32 v4, v4
	v_add_u32_e32 v5, s5, v1
	v_mul_f32_e32 v4, 0x4f7ffffe, v4
	v_cvt_u32_f32_e32 v4, v4
	v_mul_lo_u32 v1, v3, v4
	v_mul_hi_u32 v1, v4, v1
	v_add_u32_e32 v1, v4, v1
	v_mul_hi_u32 v1, v5, v1
	v_mul_lo_u32 v3, v1, v2
	v_sub_u32_e32 v3, v5, v3
	v_add_u32_e32 v4, 1, v1
	v_cmp_ge_u32_e32 vcc, v3, v2
	s_nop 1
	v_cndmask_b32_e32 v1, v1, v4, vcc
	v_sub_u32_e32 v4, v3, v2
	v_cndmask_b32_e32 v3, v3, v4, vcc
	v_add_u32_e32 v4, 1, v1
	v_cmp_ge_u32_e32 vcc, v3, v2
	v_add_u32_e32 v3, 1, v5
	s_nop 0
	v_cndmask_b32_e32 v1, v1, v4, vcc
	v_mul_lo_u32 v4, v2, v1
	v_add_u32_e32 v2, v4, v2
	v_cmp_ne_u32_e32 vcc, v3, v2
	s_and_saveexec_b64 s[14:15], vcc
	s_xor_b64 s[18:19], exec, s[14:15]
	s_cbranch_execz .LBB0_507
	s_waitcnt lgkmcnt(0)
	v_mov_b32_e32 v0, 0
	global_load_dword v2, v0, s[26:27] sc1
	s_waitcnt vmcnt(0)
	v_cmp_eq_u32_e32 vcc, v2, v1
	s_and_saveexec_b64 s[38:39], vcc
	s_cbranch_execz .LBB0_506
	s_mov_b32 s5, 1
	s_mov_b64 s[40:41], 0
	s_branch .LBB0_497

.LBB0_499:
	global_load_dword v2, v0, s[26:27] sc1
	s_add_i32 s5, s5, 1
	s_mov_b64 s[46:47], -1
	s_waitcnt vmcnt(0)
	v_cmp_ne_u32_e32 vcc, v2, v1
	s_orn2_b64 s[44:45], vcc, exec
	s_branch .LBB0_496

; __device__ __forceinline__ unsigned xb_ld(unsigned* p)              { return __hip_atomic_load(p, __ATOMIC_RELAXED, __HIP_MEMORY_SCOPE_AGENT); }
; __device__ __forceinline__ unsigned xb_add(unsigned* p, unsigned v) { return __hip_atomic_fetch_add(p, v, __ATOMIC_RELAXED, __HIP_MEMORY_SCOPE_AGENT); }
; #define XB_SPIN(cond, bar) do { unsigned _sp = 0; while (cond) { __builtin_amdgcn_s_sleep(1); \
;     if ((++_sp & 255u) == 0u) { if (xb_ld(&(bar)[XB_TMO])) break; if (_sp > XB_SPIN_CAP) { atomicAdd(&(bar)[XB_TMO], 1u); break; } } } } while (0)
; __device__ __forceinline__ void xcd_barrier(const XcdBarrier& b) {
;     ...
;         const unsigned old = xb_add(&bar[XB_XSUB(b.x)], 1u);
;         const unsigned gen = old / nloc;
;         if (old + 1u == (gen + 1u) * nloc) {
;             __builtin_amdgcn_fence(__ATOMIC_RELEASE, "agent");
;             asm volatile("s_waitcnt vmcnt(0)" ::: "memory");
;             const unsigned og = xb_add(&bar[XB_TOP], 1u);
;             const unsigned tg = og / nx;
;             if (og + 1u == (tg + 1u) * nx) xb_add(&bar[XB_TOPGEN], 1u);
;             else XB_SPIN(xb_ld(&bar[XB_TOPGEN]) == tg, bar);
;             __builtin_amdgcn_fence(__ATOMIC_ACQUIRE, "agent");
;             xb_add(&bar[XB_XGEN(b.x)], 1u);
;             asm volatile("s_waitcnt vmcnt(0)" ::: "memory");
;         } else {
;             XB_SPIN(xb_ld(&bar[XB_XGEN(b.x)]) == gen, bar);
.LBB0_702:
	s_or_b64 exec, exec, s[18:19]
	v_cvt_f32_u32_e32 v4, v2
	s_waitcnt vmcnt(0)
	v_readfirstlane_b32 s14, v3
	v_sub_u32_e32 v3, 0, v2
	v_rcp_iflag_f32_e32 v4, v4
	v_add_u32_e32 v5, s14, v1
	v_mul_f32_e32 v4, 0x4f7ffffe, v4
	v_cvt_u32_f32_e32 v4, v4
	v_mul_lo_u32 v1, v3, v4
	v_mul_hi_u32 v1, v4, v1
	v_add_u32_e32 v1, v4, v1
	v_mul_hi_u32 v1, v5, v1
	v_mul_lo_u32 v3, v1, v2
	v_sub_u32_e32 v3, v5, v3
	v_add_u32_e32 v4, 1, v1
	v_cmp_ge_u32_e32 vcc, v3, v2
	s_nop 1
	v_cndmask_b32_e32 v1, v1, v4, vcc
	v_sub_u32_e32 v4, v3, v2
	v_cndmask_b32_e32 v3, v3, v4, vcc
	v_add_u32_e32 v4, 1, v1
	v_cmp_ge_u32_e32 vcc, v3, v2
	v_add_u32_e32 v3, 1, v5
	s_nop 0
	v_cndmask_b32_e32 v1, v1, v4, vcc
	v_mul_lo_u32 v4, v2, v1
	v_add_u32_e32 v2, v4, v2
	v_cmp_ne_u32_e32 vcc, v3, v2
	s_and_saveexec_b64 s[14:15], vcc
	s_xor_b64 s[18:19], exec, s[14:15]
	s_cbranch_execz .LBB0_716
	s_waitcnt lgkmcnt(0)
	v_mov_b32_e32 v0, 0
	global_load_dword v2, v0, s[26:27] sc1
	s_waitcnt vmcnt(0)
	v_cmp_eq_u32_e32 vcc, v2, v1
	s_and_saveexec_b64 s[36:37], vcc
	s_cbranch_execz .LBB0_715
	s_mov_b32 s16, 1
	s_mov_b64 s[38:39], 0
	s_branch .LBB0_706

.LBB0_708:
	global_load_dword v2, v0, s[26:27] sc1
	s_add_i32 s16, s16, 1
	s_mov_b64 s[44:45], -1
	s_waitcnt vmcnt(0)
	v_cmp_ne_u32_e32 vcc, v2, v1
	s_orn2_b64 s[42:43], vcc, exec
	s_branch .LBB0_705

; __device__ __forceinline__ unsigned xb_ld(unsigned* p)              { return __hip_atomic_load(p, __ATOMIC_RELAXED, __HIP_MEMORY_SCOPE_AGENT); }
; __device__ __forceinline__ unsigned xb_add(unsigned* p, unsigned v) { return __hip_atomic_fetch_add(p, v, __ATOMIC_RELAXED, __HIP_MEMORY_SCOPE_AGENT); }
; #define XB_SPIN(cond, bar) do { unsigned _sp = 0; while (cond) { __builtin_amdgcn_s_sleep(1); \
;     if ((++_sp & 255u) == 0u) { if (xb_ld(&(bar)[XB_TMO])) break; if (_sp > XB_SPIN_CAP) { atomicAdd(&(bar)[XB_TMO], 1u); break; } } } } while (0)
; __device__ __forceinline__ void xcd_barrier(const XcdBarrier& b) {
;     ...
;         const unsigned old = xb_add(&bar[XB_XSUB(b.x)], 1u);
;         const unsigned gen = old / nloc;
;         if (old + 1u == (gen + 1u) * nloc) {
;             __builtin_amdgcn_fence(__ATOMIC_RELEASE, "agent");
;             asm volatile("s_waitcnt vmcnt(0)" ::: "memory");
;             const unsigned og = xb_add(&bar[XB_TOP], 1u);
;             const unsigned tg = og / nx;
;             if (og + 1u == (tg + 1u) * nx) xb_add(&bar[XB_TOPGEN], 1u);
;             else XB_SPIN(xb_ld(&bar[XB_TOPGEN]) == tg, bar);
;             __builtin_amdgcn_fence(__ATOMIC_ACQUIRE, "agent");
;             xb_add(&bar[XB_XGEN(b.x)], 1u);
;             asm volatile("s_waitcnt vmcnt(0)" ::: "memory");
;         } else {
;             XB_SPIN(xb_ld(&bar[XB_XGEN(b.x)]) == gen, bar);
.LBB0_770:
	s_or_b64 exec, exec, s[4:5]
	v_cvt_f32_u32_e32 v4, v2
	s_waitcnt vmcnt(0)
	v_readfirstlane_b32 s4, v3
	v_sub_u32_e32 v3, 0, v2
	v_rcp_iflag_f32_e32 v4, v4
	v_add_u32_e32 v5, s4, v1
	v_mul_f32_e32 v4, 0x4f7ffffe, v4
	v_cvt_u32_f32_e32 v4, v4
	v_mul_lo_u32 v1, v3, v4
	v_mul_hi_u32 v1, v4, v1
	v_add_u32_e32 v1, v4, v1
	v_mul_hi_u32 v1, v5, v1
	v_mul_lo_u32 v3, v1, v2
	v_sub_u32_e32 v3, v5, v3
	v_add_u32_e32 v4, 1, v1
	v_cmp_ge_u32_e32 vcc, v3, v2
	s_nop 1
	v_cndmask_b32_e32 v1, v1, v4, vcc
	v_sub_u32_e32 v4, v3, v2
	v_cndmask_b32_e32 v3, v3, v4, vcc
	v_add_u32_e32 v4, 1, v1
	v_cmp_ge_u32_e32 vcc, v3, v2
	v_add_u32_e32 v3, 1, v5
	s_nop 0
	v_cndmask_b32_e32 v1, v1, v4, vcc
	v_mul_lo_u32 v4, v2, v1
	v_add_u32_e32 v2, v4, v2
	v_cmp_ne_u32_e32 vcc, v3, v2
	s_and_saveexec_b64 s[4:5], vcc
	s_xor_b64 s[4:5], exec, s[4:5]
	s_cbranch_execz .LBB0_784
	s_waitcnt lgkmcnt(0)
	v_mov_b32_e32 v0, 0
	global_load_dword v2, v0, s[26:27] sc1
	s_waitcnt vmcnt(0)
	v_cmp_eq_u32_e32 vcc, v2, v1
	s_and_saveexec_b64 s[18:19], vcc
	s_cbranch_execz .LBB0_783
	s_mov_b32 s16, 1
	s_mov_b64 s[36:37], 0
	s_branch .LBB0_774

.LBB0_776:
	global_load_dword v2, v0, s[26:27] sc1
	s_add_i32 s16, s16, 1
	s_mov_b64 s[42:43], -1
	s_waitcnt vmcnt(0)
	v_cmp_ne_u32_e32 vcc, v2, v1
	s_orn2_b64 s[40:41], vcc, exec
	s_branch .LBB0_773

; __device__ __forceinline__ unsigned xb_ld(unsigned* p)              { return __hip_atomic_load(p, __ATOMIC_RELAXED, __HIP_MEMORY_SCOPE_AGENT); }
; __device__ __forceinline__ unsigned xb_add(unsigned* p, unsigned v) { return __hip_atomic_fetch_add(p, v, __ATOMIC_RELAXED, __HIP_MEMORY_SCOPE_AGENT); }
; #define XB_SPIN(cond, bar) do { unsigned _sp = 0; while (cond) { __builtin_amdgcn_s_sleep(1); \
;     if ((++_sp & 255u) == 0u) { if (xb_ld(&(bar)[XB_TMO])) break; if (_sp > XB_SPIN_CAP) { atomicAdd(&(bar)[XB_TMO], 1u); break; } } } } while (0)
; __device__ __forceinline__ void xcd_barrier(const XcdBarrier& b) {
;     ...
;         const unsigned old = xb_add(&bar[XB_XSUB(b.x)], 1u);
;         const unsigned gen = old / nloc;
;         if (old + 1u == (gen + 1u) * nloc) {
;             __builtin_amdgcn_fence(__ATOMIC_RELEASE, "agent");
;             asm volatile("s_waitcnt vmcnt(0)" ::: "memory");
;             const unsigned og = xb_add(&bar[XB_TOP], 1u);
;             const unsigned tg = og / nx;
;             if (og + 1u == (tg + 1u) * nx) xb_add(&bar[XB_TOPGEN], 1u);
;             else XB_SPIN(xb_ld(&bar[XB_TOPGEN]) == tg, bar);
;             __builtin_amdgcn_fence(__ATOMIC_ACQUIRE, "agent");
;             xb_add(&bar[XB_XGEN(b.x)], 1u);
;             asm volatile("s_waitcnt vmcnt(0)" ::: "memory");
;         } else {
;             XB_SPIN(xb_ld(&bar[XB_XGEN(b.x)]) == gen, bar);
.LBB0_944:
	s_or_b64 exec, exec, s[4:5]
	v_cvt_f32_u32_e32 v4, v2
	s_waitcnt vmcnt(0)
	v_readfirstlane_b32 s4, v3
	v_sub_u32_e32 v3, 0, v2
	v_rcp_iflag_f32_e32 v4, v4
	v_add_u32_e32 v5, s4, v1
	v_mul_f32_e32 v4, 0x4f7ffffe, v4
	v_cvt_u32_f32_e32 v4, v4
	v_mul_lo_u32 v1, v3, v4
	v_mul_hi_u32 v1, v4, v1
	v_add_u32_e32 v1, v4, v1
	v_mul_hi_u32 v1, v5, v1
	v_mul_lo_u32 v3, v1, v2
	v_sub_u32_e32 v3, v5, v3
	v_add_u32_e32 v4, 1, v1
	v_cmp_ge_u32_e32 vcc, v3, v2
	s_nop 1
	v_cndmask_b32_e32 v1, v1, v4, vcc
	v_sub_u32_e32 v4, v3, v2
	v_cndmask_b32_e32 v3, v3, v4, vcc
	v_add_u32_e32 v4, 1, v1
	v_cmp_ge_u32_e32 vcc, v3, v2
	v_add_u32_e32 v3, 1, v5
	s_nop 0
	v_cndmask_b32_e32 v1, v1, v4, vcc
	v_mul_lo_u32 v4, v2, v1
	v_add_u32_e32 v2, v4, v2
	v_cmp_ne_u32_e32 vcc, v3, v2
	s_and_saveexec_b64 s[4:5], vcc
	s_xor_b64 s[4:5], exec, s[4:5]
	s_cbranch_execz .LBB0_958
	s_waitcnt lgkmcnt(0)
	v_mov_b32_e32 v0, 0
	global_load_dword v2, v0, s[26:27] sc1
	s_waitcnt vmcnt(0)
	v_cmp_eq_u32_e32 vcc, v2, v1
	s_and_saveexec_b64 s[14:15], vcc
	s_cbranch_execz .LBB0_957
	s_mov_b64 s[28:29], s[26:27]
	s_mov_b32 s26, 1
	s_mov_b64 s[16:17], 0
	s_branch .LBB0_948

.LBB0_950:
	global_load_dword v2, v0, s[28:29] sc1
	s_add_i32 s26, s26, 1
	s_mov_b64 s[22:23], -1
	s_waitcnt vmcnt(0)
	v_cmp_ne_u32_e32 vcc, v2, v1
	s_orn2_b64 s[20:21], vcc, exec
	s_branch .LBB0_947
